# preflush-by-second-to-last-arriver
# speedup vs baseline: 1.0046x; 1.0046x over previous
.Lsbar_nl:
	v_add_u32_e32 v249, 1, v249
	v_cmp_eq_u32_e32 vcc, v249, v245
	s_cbranch_vccz .Lsbar_poll
	buffer_wbl2 sc1
